# v22 + LoRA stage-2 GEMM runs 2 of 4 k-tiles: its K is zero-padded 96 to 256 on both operands by this kernel's own layout, result bit-identical
# speedup vs baseline: 1.0344x; 1.0053x over previous
; #define WAIT_V(n) asm volatile("s_waitcnt vmcnt(" #n ")" ::: "memory")
; #define BAR __builtin_amdgcn_s_barrier()
; __device__ __forceinline__ void gemm_tile(const TileDesc& td, unsigned char* lds) {
;     ...
;     f32x4 acc[2][2][4][2] = {};
;     bf16x8 At[4][2], B0[2][2], B1[2][2];
;     const int nt = __builtin_amdgcn_readfirstlane(td.K) / BK;
;     STAGE(SB(0, 0), Bt, ldb, bcol, 0); STAGE(SA(0, 0), A, lda, brow, 0);
;     STAGE(SB(0, 1), Bt, ldb, bcol + HALF, 0); STAGE(SA(0, 1), A, lda, brow + HALF, 0);
;     if (wr == 1) BAR;
;     WAIT_V(4); BAR;
;     STAGE(SB(1, 0), Bt, ldb, bcol, 1); STAGE(SA(1, 0), A, lda, brow, 1); STAGE(SB(1, 1), Bt, ldb, bcol + HALF, 1);
;     WAIT_V(6); BAR;
;     for (int t = 0; t < nt - 2; t += 2) {
; __device__ __forceinline__ void phase_gemm(const Params& p, int kind, int j, unsigned char* lds) {
;     ...
;             td.A = (const bf16_t*)(big + B_LORA) + job * 256; td.lda = 1280; td.Bt = wtb + WT_R_L2 / 2 + (size_t)job * D * 256; td.ldb = 256; td.K = 256;
.LBB0_243:
	s_or_b64 exec, exec, s[6:7]
	v_readlane_b32 s2, v254, 4
	s_add_u32 s6, s18, 0x80
	s_addc_u32 s7, s19, 0
	v_add_u32_e32 v176, s2, v0
	v_mov_b32_e32 v137, v133
	v_readfirstlane_b32 s2, v176
	v_lshl_add_u64 v[2:3], s[6:7], 0, v[132:133]
	s_mov_b32 m0, s2
	v_add_u32_e32 v177, 0x2000, v176
	s_waitcnt vmcnt(4)
	s_barrier
	global_load_lds_dwordx4 v[2:3], off
	v_lshl_add_u64 v[2:3], s[6:7], 0, v[136:137]
	v_readfirstlane_b32 s2, v177
	s_add_u32 s6, s24, 0x80
	v_add_u32_e32 v178, 0x8000, v139
	v_mov_b32_e32 v129, v133
	s_mov_b32 m0, s2
	s_addc_u32 s7, s25, 0
	v_readfirstlane_b32 s2, v178
	v_add_u32_e32 v179, 0xa000, v139
	global_load_lds_dwordx4 v[2:3], off
	v_lshl_add_u64 v[2:3], s[6:7], 0, v[128:129]
	s_mov_b32 m0, s2
	v_readfirstlane_b32 s2, v179
	v_mov_b32_e32 v131, v133
	global_load_lds_dwordx4 v[2:3], off
	s_mov_b32 m0, s2
	v_readlane_b32 s2, v254, 5
	v_lshl_add_u64 v[2:3], s[6:7], 0, v[130:131]
	s_add_u32 s6, s80, 0x80
	v_add_u32_e32 v180, s2, v0
	s_addc_u32 s7, s81, 0
	v_readfirstlane_b32 s2, v180
	v_add_u32_e32 v181, 0x2000, v180
	global_load_lds_dwordx4 v[2:3], off
	v_lshl_add_u64 v[2:3], s[6:7], 0, v[132:133]
	s_mov_b32 m0, s2
	v_readfirstlane_b32 s2, v181
	global_load_lds_dwordx4 v[2:3], off
	v_lshl_add_u64 v[2:3], s[6:7], 0, v[136:137]
	s_mov_b32 m0, s2
	v_and_b32_e32 v0, 15, v134
	global_load_lds_dwordx4 v[2:3], off
	s_waitcnt vmcnt(6)
	v_lshlrev_b32_e32 v2, 6, v134
	v_lshlrev_b32_e32 v187, 6, v0
	v_lshlrev_b32_e32 v0, 2, v0
	v_and_b32_e32 v186, 48, v134
	s_cmpk_lg_i32 s30, 0x500
	v_and_b32_e32 v138, 0x3000, v2
	s_mov_b64 s[30:31], -1
	v_lshlrev_b32_e32 v154, 13, v1
	v_and_b32_e32 v188, 32, v0
	s_barrier
	s_cbranch_scc1 .LBB0_245
	v_lshlrev_b32_e32 v185, 13, v1
	v_or_b32_e32 v182, 0x400, v138
	v_or_b32_e32 v183, 0x800, v138
	v_or_b32_e32 v184, 0xc00, v138
	v_bitop3_b32 v142, v187, v188, v186 bitop3:0x36
	v_or_b32_e32 v144, 0x400, v185
	v_or_b32_e32 v145, 0x800, v185
	v_or_b32_e32 v146, 0xc00, v185
	v_or_b32_e32 v147, 0x1000, v185
	v_or_b32_e32 v148, 0x1400, v185
	v_or_b32_e32 v149, 0x1800, v185
	v_or_b32_e32 v150, 0x1c00, v185
	s_mov_b64 s[30:31], 0
.LBB0_245:
	s_ashr_i32 s2, s3, 31
	s_lshr_b32 s2, s2, 26
	v_lshlrev_b32_e32 v0, 2, v134
	s_add_i32 s2, s3, s2
	v_and_b32_e32 v0, 32, v0
	s_ashr_i32 s6, s2, 6
	s_cmp_eq_u32 s30, 0
	s_cselect_b32 s6, 2, s6
	v_bitop3_b32 v0, v187, v0, v186 bitop3:0x36
	v_readlane_b32 s2, v254, 2
	v_mov_b32_e32 v103, 0
	s_andn2_b64 vcc, exec, s[30:31]
	v_add_u32_e32 v151, s2, v0
	v_readlane_b32 s2, v254, 3
	v_mov_b32_e32 v102, v103
	v_mov_b32_e32 v101, v103
	v_add_u32_e32 v143, s2, v0
	v_readlane_b32 s2, v254, 4
	v_mov_b32_e32 v100, v103
	v_mov_b32_e32 v127, v103
	v_add_u32_e32 v141, s2, v0
	v_readlane_b32 s2, v254, 5
	v_mov_b32_e32 v126, v103
	v_mov_b32_e32 v125, v103
	v_add_u32_e32 v140, s2, v0
	v_mov_b32_e32 v124, v103
	v_mov_b32_e32 v123, v103
	v_mov_b32_e32 v122, v103
	v_mov_b32_e32 v121, v103
	v_mov_b32_e32 v120, v103
	v_mov_b32_e32 v119, v103
	v_mov_b32_e32 v118, v103
	v_mov_b32_e32 v117, v103
	v_mov_b32_e32 v116, v103
	s_waitcnt vmcnt(0)
	v_mov_b32_e32 v115, v103
	v_mov_b32_e32 v114, v103
	v_mov_b32_e32 v113, v103
	v_mov_b32_e32 v112, v103
	v_mov_b32_e32 v111, v103
	v_mov_b32_e32 v110, v103
	v_mov_b32_e32 v109, v103
	v_mov_b32_e32 v108, v103
	v_mov_b32_e32 v107, v103
	v_mov_b32_e32 v106, v103
	v_mov_b32_e32 v105, v103
	v_mov_b32_e32 v104, v103
	v_mov_b32_e32 v99, v103
	v_mov_b32_e32 v98, v103
	v_mov_b32_e32 v97, v103
	v_mov_b32_e32 v96, v103
	v_mov_b32_e32 v95, v103
	v_mov_b32_e32 v94, v103
	v_mov_b32_e32 v93, v103
	v_mov_b32_e32 v92, v103
	v_mov_b32_e32 v91, v103
	v_mov_b32_e32 v90, v103
	v_mov_b32_e32 v89, v103
	v_mov_b32_e32 v88, v103
	v_mov_b32_e32 v87, v103
	v_mov_b32_e32 v86, v103
	v_mov_b32_e32 v85, v103
	v_mov_b32_e32 v84, v103
	v_mov_b32_e32 v83, v103
	v_mov_b32_e32 v82, v103
	v_mov_b32_e32 v81, v103
	v_mov_b32_e32 v80, v103
	v_mov_b32_e32 v79, v103
	v_mov_b32_e32 v78, v103
	v_mov_b32_e32 v77, v103
	v_mov_b32_e32 v76, v103
	v_mov_b32_e32 v75, v103
	v_mov_b32_e32 v74, v103
	v_mov_b32_e32 v73, v103
	v_mov_b32_e32 v72, v103
	v_mov_b32_e32 v71, v103
	v_mov_b32_e32 v70, v103
	v_mov_b32_e32 v69, v103
	v_mov_b32_e32 v68, v103
	v_mov_b32_e32 v67, v103
	v_mov_b32_e32 v66, v103
	v_mov_b32_e32 v65, v103
	v_mov_b32_e32 v64, v103
	v_mov_b32_e32 v63, v103
	v_mov_b32_e32 v62, v103
	v_mov_b32_e32 v61, v103
	v_mov_b32_e32 v60, v103
	v_mov_b32_e32 v59, v103
	v_mov_b32_e32 v58, v103
	v_mov_b32_e32 v57, v103
	v_mov_b32_e32 v56, v103
	v_mov_b32_e32 v55, v103
	v_mov_b32_e32 v54, v103
	v_mov_b32_e32 v53, v103
	v_mov_b32_e32 v52, v103
	v_mov_b32_e32 v51, v103
	v_mov_b32_e32 v50, v103
	v_mov_b32_e32 v49, v103
	v_mov_b32_e32 v48, v103
	v_mov_b32_e32 v47, v103
	v_mov_b32_e32 v46, v103
	v_mov_b32_e32 v45, v103
	v_mov_b32_e32 v44, v103
	v_mov_b32_e32 v43, v103
	v_mov_b32_e32 v42, v103
	v_mov_b32_e32 v41, v103
	v_mov_b32_e32 v40, v103
	v_mov_b32_e32 v39, v103
	v_mov_b32_e32 v38, v103
	v_mov_b32_e32 v37, v103
	v_mov_b32_e32 v36, v103
	v_mov_b32_e32 v35, v103
	v_mov_b32_e32 v34, v103
	v_mov_b32_e32 v33, v103
	v_mov_b32_e32 v32, v103
	v_mov_b32_e32 v31, v103
	v_mov_b32_e32 v30, v103
	v_mov_b32_e32 v29, v103
	v_mov_b32_e32 v28, v103
	v_mov_b32_e32 v27, v103
	v_mov_b32_e32 v26, v103
	v_mov_b32_e32 v25, v103
	v_mov_b32_e32 v24, v103
	v_mov_b32_e32 v23, v103
	v_mov_b32_e32 v22, v103
	v_mov_b32_e32 v21, v103
	v_mov_b32_e32 v20, v103
	v_mov_b32_e32 v19, v103
	v_mov_b32_e32 v18, v103
	v_mov_b32_e32 v17, v103
	v_mov_b32_e32 v16, v103
	v_mov_b32_e32 v15, v103
	v_mov_b32_e32 v14, v103
	v_mov_b32_e32 v13, v103
	v_mov_b32_e32 v12, v103
	v_mov_b32_e32 v11, v103
	v_mov_b32_e32 v10, v103
	v_mov_b32_e32 v9, v103
	v_mov_b32_e32 v8, v103
	v_mov_b32_e32 v7, v103
	v_mov_b32_e32 v6, v103
	v_mov_b32_e32 v5, v103
	v_mov_b32_e32 v4, v103
	v_mov_b32_e32 v3, v103
	v_mov_b32_e32 v2, v103
	v_mov_b32_e32 v1, v103
	v_mov_b32_e32 v0, v103
	s_cbranch_vccnz .LBB0_249
; #define WAIT_V(n) asm volatile("s_waitcnt vmcnt(" #n ")" ::: "memory")
; #define BAR __builtin_amdgcn_s_barrier()
; __device__ __forceinline__ void gemm_tile(const TileDesc& td, unsigned char* lds) {
;     ...
;     f32x4 acc[2][2][4][2] = {};
;     bf16x8 At[4][2], B0[2][2], B1[2][2];
;     const int nt = __builtin_amdgcn_readfirstlane(td.K) / BK;
;     STAGE(SB(0, 0), Bt, ldb, bcol, 0); STAGE(SA(0, 0), A, lda, brow, 0);
;     STAGE(SB(0, 1), Bt, ldb, bcol + HALF, 0); STAGE(SA(0, 1), A, lda, brow + HALF, 0);
;     if (wr == 1) BAR;
;     WAIT_V(4); BAR;
;     STAGE(SB(1, 0), Bt, ldb, bcol, 1); STAGE(SA(1, 0), A, lda, brow, 1); STAGE(SB(1, 1), Bt, ldb, bcol + HALF, 1);
;     WAIT_V(6); BAR;
;     for (int t = 0; t < nt - 2; t += 2) {
	v_bitop3_b32 v142, v187, v188, v186 bitop3:0x36
	v_add_u32_e32 v182, 0, v142
	v_or_b32_e32 v145, 0x800, v154
	v_or_b32_e32 v147, 0x1000, v154
	v_or_b32_e32 v149, 0x1800, v154
	v_mov_b32_e32 v0, 0
	v_mov_b32_e32 v171, v135
	v_mov_b32_e32 v135, 0x2000
	v_mov_b32_e32 v167, 0x300000
	v_mov_b32_e32 v165, 0x358637bd
	v_mov_b32_e32 v250, 0x7fc00000
	v_mov_b32_e32 v173, 0x1000
	v_mov_b32_e32 v170, 0x3f1b4598
	v_mov_b32_e32 v172, 1
	v_mov_b32_e32 v251, 0x1fff
	v_mov_b32_e32 v159, 0xfff
	s_add_i32 s2, s6, -2
	v_or_b32_e32 v144, 0x400, v154
	v_or_b32_e32 v146, 0xc00, v154
	v_or_b32_e32 v148, 0x1400, v154
	v_or_b32_e32 v150, 0x1c00, v154
	s_mov_b32 s3, 0
	s_mov_b64 s[78:79], 0
	v_add_u32_e32 v183, v151, v138
	v_add_u32_e32 v184, v182, v145
	v_add_u32_e32 v185, v182, v147
	v_add_u32_e32 v186, v182, v149
	v_add_u32_e32 v187, v143, v138
	v_add_u32_e32 v188, v141, v138
	v_add_u32_e32 v189, v140, v138
	v_mov_b32_e32 v1, v0
	v_mov_b32_e32 v2, v0
	v_mov_b32_e32 v3, v0
	v_mov_b32_e32 v4, v0
	v_mov_b32_e32 v5, v0
	v_mov_b32_e32 v6, v0
	v_mov_b32_e32 v7, v0
	v_mov_b32_e32 v8, v0
	v_mov_b32_e32 v9, v0
	v_mov_b32_e32 v10, v0
	v_mov_b32_e32 v11, v0
	v_mov_b32_e32 v12, v0
	v_mov_b32_e32 v13, v0
	v_mov_b32_e32 v14, v0
	v_mov_b32_e32 v15, v0
	v_mov_b32_e32 v16, v0
	v_mov_b32_e32 v17, v0
	v_mov_b32_e32 v18, v0
	v_mov_b32_e32 v19, v0
	v_mov_b32_e32 v20, v0
	v_mov_b32_e32 v21, v0
	v_mov_b32_e32 v22, v0
	v_mov_b32_e32 v23, v0
	v_mov_b32_e32 v24, v0
	v_mov_b32_e32 v25, v0
	v_mov_b32_e32 v26, v0
	v_mov_b32_e32 v27, v0
	v_mov_b32_e32 v28, v0
	v_mov_b32_e32 v29, v0
	v_mov_b32_e32 v30, v0
	v_mov_b32_e32 v31, v0
	v_mov_b32_e32 v32, v0
	v_mov_b32_e32 v33, v0
	v_mov_b32_e32 v34, v0
	v_mov_b32_e32 v35, v0
	v_mov_b32_e32 v36, v0
	v_mov_b32_e32 v37, v0
	v_mov_b32_e32 v38, v0
	v_mov_b32_e32 v39, v0
	v_mov_b32_e32 v40, v0
	v_mov_b32_e32 v41, v0
	v_mov_b32_e32 v42, v0
	v_mov_b32_e32 v43, v0
	v_mov_b32_e32 v44, v0
	v_mov_b32_e32 v45, v0
	v_mov_b32_e32 v46, v0
	v_mov_b32_e32 v47, v0
	v_mov_b32_e32 v48, v0
	v_mov_b32_e32 v49, v0
	v_mov_b32_e32 v50, v0
	v_mov_b32_e32 v51, v0
	v_mov_b32_e32 v52, v0
	v_mov_b32_e32 v53, v0
	v_mov_b32_e32 v54, v0
	v_mov_b32_e32 v55, v0
	v_mov_b32_e32 v56, v0
	v_mov_b32_e32 v57, v0
	v_mov_b32_e32 v58, v0
	v_mov_b32_e32 v59, v0
	v_mov_b32_e32 v60, v0
	v_mov_b32_e32 v61, v0
	v_mov_b32_e32 v62, v0
	v_mov_b32_e32 v63, v0
	v_mov_b32_e32 v64, v0
	v_mov_b32_e32 v65, v0
	v_mov_b32_e32 v66, v0
	v_mov_b32_e32 v67, v0
	v_mov_b32_e32 v68, v0
	v_mov_b32_e32 v69, v0
	v_mov_b32_e32 v70, v0
	v_mov_b32_e32 v71, v0
	v_mov_b32_e32 v72, v0
	v_mov_b32_e32 v73, v0
	v_mov_b32_e32 v74, v0
	v_mov_b32_e32 v75, v0
	v_mov_b32_e32 v76, v0
	v_mov_b32_e32 v77, v0
	v_mov_b32_e32 v78, v0
	v_mov_b32_e32 v79, v0
	v_mov_b32_e32 v80, v0
	v_mov_b32_e32 v81, v0
	v_mov_b32_e32 v82, v0
	v_mov_b32_e32 v83, v0
	v_mov_b32_e32 v84, v0
	v_mov_b32_e32 v85, v0
	v_mov_b32_e32 v86, v0
	v_mov_b32_e32 v87, v0
	v_mov_b32_e32 v88, v0
	v_mov_b32_e32 v89, v0
	v_mov_b32_e32 v90, v0
	v_mov_b32_e32 v91, v0
	v_mov_b32_e32 v92, v0
	v_mov_b32_e32 v93, v0
	v_mov_b32_e32 v94, v0
	v_mov_b32_e32 v95, v0
	v_mov_b32_e32 v96, v0
	v_mov_b32_e32 v97, v0
	v_mov_b32_e32 v98, v0
	v_mov_b32_e32 v99, v0
	v_mov_b32_e32 v104, v0
	v_mov_b32_e32 v105, v0
	v_mov_b32_e32 v106, v0
	v_mov_b32_e32 v107, v0
	v_mov_b32_e32 v108, v0
	v_mov_b32_e32 v109, v0
	v_mov_b32_e32 v110, v0
	v_mov_b32_e32 v111, v0
	v_mov_b32_e32 v112, v0
	v_mov_b32_e32 v113, v0
	v_mov_b32_e32 v114, v0
	v_mov_b32_e32 v115, v0
	v_mov_b32_e32 v116, v0
	v_mov_b32_e32 v117, v0
	v_mov_b32_e32 v118, v0
	v_mov_b32_e32 v119, v0
	v_mov_b32_e32 v120, v0
	v_mov_b32_e32 v121, v0
	v_mov_b32_e32 v122, v0
	v_mov_b32_e32 v123, v0
	v_mov_b32_e32 v124, v0
	v_mov_b32_e32 v125, v0
	v_mov_b32_e32 v126, v0
	v_mov_b32_e32 v127, v0
	v_mov_b32_e32 v100, v0
	v_mov_b32_e32 v101, v0
	v_mov_b32_e32 v102, v0
	v_mov_b32_e32 v103, v0
